# static s_setprio 1 for block id >= 256 extended through attention/dn_chunk phase (reset at scan), plus GEMM-2/3
# speedup vs baseline: 1.0101x; 1.0101x over previous
.LBB0_302:
	s_setprio 0
	s_mov_b32 s27, s96
